# speedup vs baseline: 1.0066x; 1.0011x over previous
.LBB0_345:
	v_lshl_add_u32 v144, s8, 8, v152
	v_lshlrev_b32_e32 v232, 2, v144
	global_load_dword v233, v232, s[66:67]
	global_load_dword v234, v232, s[66:67] offset:64
	global_load_dword v235, v232, s[66:67] offset:128
	global_load_dword v236, v232, s[66:67] offset:192
	global_load_dword v237, v232, s[66:67] offset:512
	global_load_dword v238, v232, s[66:67] offset:576
	global_load_dword v239, v232, s[66:67] offset:640
	global_load_dword v240, v232, s[66:67] offset:704
	v_ashrrev_i32_e32 v145, 31, v144
	v_lshl_add_u64 v[142:143], v[144:145], 2, s[66:67]
	s_nop 0
	v_lshl_or_b32 v142, s6, 8, v154
	v_mul_hi_i32 v143, v142, s74
	v_lshlrev_b64 v[146:147], 8, v[144:145]
	v_lshrrev_b32_e32 v145, 31, v143
	v_lshrrev_b32_e32 v143, 5, v143
	v_add_u32_e32 v143, v143, v145
	v_mul_lo_u32 v143, v143, s47
	v_sub_u32_e32 v143, v142, v143
	v_cmp_lt_i32_e32 vcc, s82, v143
	v_add_u32_e32 v143, 0xffffff80, v143
	v_lshl_add_u64 v[146:147], s[16:17], 0, v[146:147]
	s_waitcnt vmcnt(0)
	v_mov_b32_e32 v132, v233
	v_mul_f32_e32 v148, 0x3dd53b94, v132
	v_pk_mul_f32 v[126:127], v[126:127], v[148:149] op_sel_hi:[1,0]
	v_pk_mul_f32 v[124:125], v[124:125], v[148:149] op_sel_hi:[1,0]
	v_lshrrev_b32_e32 v132, 1, v143
	s_and_saveexec_b64 s[6:7], vcc
	s_cbranch_execz .LBB0_347
	v_lshl_add_u64 v[150:151], v[132:133], 3, v[146:147]
	global_load_dwordx4 v[158:161], v[150:151], off
	s_waitcnt vmcnt(0)
	v_pk_mul_f32 v[162:163], v[124:125], v[158:159] op_sel:[1,1] op_sel_hi:[0,1]
	v_mul_f32_e32 v164, v127, v161
	v_mul_f32_e32 v166, v126, v161
	v_pk_mul_f32 v[150:151], v[124:125], v[158:159]
	v_pk_fma_f32 v[124:125], v[124:125], v[158:159], v[162:163] op_sel_hi:[1,0,1]
	v_pk_fma_f32 v[158:159], v[126:127], v[160:161], v[164:165] op_sel_hi:[1,1,0] neg_lo:[0,0,1] neg_hi:[0,0,1]
	v_pk_fma_f32 v[160:161], v[126:127], v[160:161], v[166:167] op_sel:[1,0,0] op_sel_hi:[0,1,0]
	v_sub_f32_e32 v124, v150, v162
	v_mov_b32_e32 v126, v158
	v_mov_b32_e32 v127, v160

.LBB0_353:
	s_or_b64 exec, exec, s[36:37]
	v_cvt_pk_bf16_f32 v114, v114, v115
	v_cvt_pk_bf16_f32 v115, v118, v119
	v_or_b32_e32 v118, 16, v144
	v_ashrrev_i32_e32 v119, 31, v118
	global_store_dwordx2 v[124:125], v[114:115], off offset:288
	v_lshl_add_u64 v[114:115], v[118:119], 2, s[66:67]
	v_mov_b32_e32 v113, v234
	v_lshlrev_b64 v[124:125], 8, v[118:119]
	v_mul_f32_e32 v114, 0x3dd53b94, v113
	v_pk_mul_f32 v[122:123], v[110:111], v[114:115] op_sel_hi:[1,0]
	v_pk_mul_f32 v[110:111], v[108:109], v[114:115] op_sel_hi:[1,0]
	v_lshl_add_u64 v[108:109], s[16:17], 0, v[124:125]
	s_and_saveexec_b64 s[36:37], vcc
	s_cbranch_execz .LBB0_355
	v_lshl_add_u64 v[124:125], v[132:133], 3, v[108:109]
	global_load_dwordx4 v[124:127], v[124:125], off
	s_waitcnt vmcnt(0)
	v_pk_mul_f32 v[148:149], v[110:111], v[124:125] op_sel:[1,1] op_sel_hi:[0,1]
	v_mul_f32_e32 v150, v123, v127
	v_mul_f32_e32 v158, v122, v127
	v_pk_mul_f32 v[146:147], v[110:111], v[124:125]
	v_pk_fma_f32 v[110:111], v[110:111], v[124:125], v[148:149] op_sel_hi:[1,0,1]
	v_pk_fma_f32 v[124:125], v[122:123], v[126:127], v[150:151] op_sel_hi:[1,1,0] neg_lo:[0,0,1] neg_hi:[0,0,1]
	v_pk_fma_f32 v[126:127], v[122:123], v[126:127], v[158:159] op_sel:[1,0,0] op_sel_hi:[0,1,0]
	v_sub_f32_e32 v110, v146, v148
	v_mov_b32_e32 v122, v124
	v_mov_b32_e32 v123, v126

.LBB0_361:
	s_or_b64 exec, exec, s[36:37]
	v_cvt_pk_bf16_f32 v96, v96, v97
	v_cvt_pk_bf16_f32 v97, v98, v99
	v_or_b32_e32 v98, 32, v144
	v_ashrrev_i32_e32 v99, 31, v98
	global_store_dwordx2 v[110:111], v[96:97], off offset:288
	v_lshl_add_u64 v[96:97], v[98:99], 2, s[66:67]
	v_mov_b32_e32 v96, v235
	v_lshlrev_b64 v[102:103], 8, v[98:99]
	v_mul_f32_e32 v96, 0x3dd53b94, v96
	v_pk_mul_f32 v[100:101], v[94:95], v[96:97] op_sel_hi:[1,0]
	v_pk_mul_f32 v[94:95], v[92:93], v[96:97] op_sel_hi:[1,0]
	v_lshl_add_u64 v[92:93], s[16:17], 0, v[102:103]
	s_and_saveexec_b64 s[36:37], vcc
	s_cbranch_execz .LBB0_363
	v_lshl_add_u64 v[102:103], v[132:133], 3, v[92:93]
	global_load_dwordx4 v[102:105], v[102:103], off
	s_waitcnt vmcnt(0)
	v_pk_mul_f32 v[108:109], v[94:95], v[102:103] op_sel:[1,1] op_sel_hi:[0,1]
	v_mul_f32_e32 v110, v101, v105
	v_mul_f32_e32 v114, v100, v105
	v_pk_mul_f32 v[106:107], v[94:95], v[102:103]
	v_pk_fma_f32 v[94:95], v[94:95], v[102:103], v[108:109] op_sel_hi:[1,0,1]
	v_pk_fma_f32 v[102:103], v[100:101], v[104:105], v[110:111] op_sel_hi:[1,1,0] neg_lo:[0,0,1] neg_hi:[0,0,1]
	v_pk_fma_f32 v[104:105], v[100:101], v[104:105], v[114:115] op_sel:[1,0,0] op_sel_hi:[0,1,0]
	v_sub_f32_e32 v94, v106, v108
	v_mov_b32_e32 v100, v102
	v_mov_b32_e32 v101, v104

.LBB0_369:
	s_or_b64 exec, exec, s[36:37]
	v_cvt_pk_bf16_f32 v80, v80, v81
	v_cvt_pk_bf16_f32 v81, v82, v83
	v_or_b32_e32 v82, 48, v144
	v_ashrrev_i32_e32 v83, 31, v82
	global_store_dwordx2 v[94:95], v[80:81], off offset:288
	v_lshl_add_u64 v[80:81], v[82:83], 2, s[66:67]
	v_mov_b32_e32 v80, v236
	v_lshlrev_b64 v[86:87], 8, v[82:83]
	v_mul_f32_e32 v80, 0x3dd53b94, v80
	v_pk_mul_f32 v[84:85], v[78:79], v[80:81] op_sel_hi:[1,0]
	v_pk_mul_f32 v[78:79], v[76:77], v[80:81] op_sel_hi:[1,0]
	v_lshl_add_u64 v[76:77], s[16:17], 0, v[86:87]
	s_and_saveexec_b64 s[36:37], vcc
	s_cbranch_execz .LBB0_371
	v_lshl_add_u64 v[86:87], v[132:133], 3, v[76:77]
	global_load_dwordx4 v[86:89], v[86:87], off
	s_waitcnt vmcnt(0)
	v_pk_mul_f32 v[92:93], v[78:79], v[86:87] op_sel:[1,1] op_sel_hi:[0,1]
	v_mul_f32_e32 v94, v85, v89
	v_mul_f32_e32 v96, v84, v89
	v_pk_mul_f32 v[90:91], v[78:79], v[86:87]
	v_pk_fma_f32 v[78:79], v[78:79], v[86:87], v[92:93] op_sel_hi:[1,0,1]
	v_pk_fma_f32 v[86:87], v[84:85], v[88:89], v[94:95] op_sel_hi:[1,1,0] neg_lo:[0,0,1] neg_hi:[0,0,1]
	v_pk_fma_f32 v[88:89], v[84:85], v[88:89], v[96:97] op_sel:[1,0,0] op_sel_hi:[0,1,0]
	v_sub_f32_e32 v78, v90, v92
	v_mov_b32_e32 v84, v86
	v_mov_b32_e32 v85, v88

.LBB0_377:
	s_or_b64 exec, exec, s[36:37]
	v_cvt_pk_bf16_f32 v64, v64, v65
	v_cvt_pk_bf16_f32 v65, v66, v67
	v_add_u32_e32 v66, 0x80, v144
	v_ashrrev_i32_e32 v67, 31, v66
	global_store_dwordx2 v[78:79], v[64:65], off offset:288
	v_lshl_add_u64 v[64:65], v[66:67], 2, s[66:67]
	v_mov_b32_e32 v64, v237
	v_lshlrev_b64 v[70:71], 8, v[66:67]
	v_mul_f32_e32 v64, 0x3dd53b94, v64
	v_pk_mul_f32 v[68:69], v[62:63], v[64:65] op_sel_hi:[1,0]
	v_pk_mul_f32 v[62:63], v[60:61], v[64:65] op_sel_hi:[1,0]
	v_lshl_add_u64 v[60:61], s[16:17], 0, v[70:71]
	s_and_saveexec_b64 s[36:37], vcc
	s_cbranch_execz .LBB0_379
	v_lshl_add_u64 v[70:71], v[132:133], 3, v[60:61]
	global_load_dwordx4 v[70:73], v[70:71], off
	s_waitcnt vmcnt(0)
	v_pk_mul_f32 v[76:77], v[62:63], v[70:71] op_sel:[1,1] op_sel_hi:[0,1]
	v_mul_f32_e32 v78, v69, v73
	v_mul_f32_e32 v80, v68, v73
	v_pk_mul_f32 v[74:75], v[62:63], v[70:71]
	v_pk_fma_f32 v[62:63], v[62:63], v[70:71], v[76:77] op_sel_hi:[1,0,1]
	v_pk_fma_f32 v[70:71], v[68:69], v[72:73], v[78:79] op_sel_hi:[1,1,0] neg_lo:[0,0,1] neg_hi:[0,0,1]
	v_pk_fma_f32 v[72:73], v[68:69], v[72:73], v[80:81] op_sel:[1,0,0] op_sel_hi:[0,1,0]
	v_sub_f32_e32 v62, v74, v76
	v_mov_b32_e32 v68, v70
	v_mov_b32_e32 v69, v72

.LBB0_385:
	s_or_b64 exec, exec, s[36:37]
	v_cvt_pk_bf16_f32 v48, v48, v49
	v_cvt_pk_bf16_f32 v49, v50, v51
	v_add_u32_e32 v50, 0x90, v144
	v_ashrrev_i32_e32 v51, 31, v50
	global_store_dwordx2 v[62:63], v[48:49], off offset:288
	v_lshl_add_u64 v[48:49], v[50:51], 2, s[66:67]
	v_mov_b32_e32 v48, v238
	v_lshlrev_b64 v[54:55], 8, v[50:51]
	v_mul_f32_e32 v48, 0x3dd53b94, v48
	v_pk_mul_f32 v[52:53], v[46:47], v[48:49] op_sel_hi:[1,0]
	v_pk_mul_f32 v[46:47], v[44:45], v[48:49] op_sel_hi:[1,0]
	v_lshl_add_u64 v[44:45], s[16:17], 0, v[54:55]
	s_and_saveexec_b64 s[36:37], vcc
	s_cbranch_execz .LBB0_387
	v_lshl_add_u64 v[54:55], v[132:133], 3, v[44:45]
	global_load_dwordx4 v[54:57], v[54:55], off
	s_waitcnt vmcnt(0)
	v_pk_mul_f32 v[60:61], v[46:47], v[54:55] op_sel:[1,1] op_sel_hi:[0,1]
	v_mul_f32_e32 v62, v53, v57
	v_mul_f32_e32 v64, v52, v57
	v_pk_mul_f32 v[58:59], v[46:47], v[54:55]
	v_pk_fma_f32 v[46:47], v[46:47], v[54:55], v[60:61] op_sel_hi:[1,0,1]
	v_pk_fma_f32 v[54:55], v[52:53], v[56:57], v[62:63] op_sel_hi:[1,1,0] neg_lo:[0,0,1] neg_hi:[0,0,1]
	v_pk_fma_f32 v[56:57], v[52:53], v[56:57], v[64:65] op_sel:[1,0,0] op_sel_hi:[0,1,0]
	v_sub_f32_e32 v46, v58, v60
	v_mov_b32_e32 v52, v54
	v_mov_b32_e32 v53, v56

.LBB0_393:
	s_or_b64 exec, exec, s[36:37]
	v_cvt_pk_bf16_f32 v32, v32, v33
	v_cvt_pk_bf16_f32 v33, v34, v35
	v_add_u32_e32 v34, 0xa0, v144
	v_ashrrev_i32_e32 v35, 31, v34
	global_store_dwordx2 v[46:47], v[32:33], off offset:288
	v_lshl_add_u64 v[32:33], v[34:35], 2, s[66:67]
	v_mov_b32_e32 v32, v239
	v_lshlrev_b64 v[38:39], 8, v[34:35]
	v_mul_f32_e32 v32, 0x3dd53b94, v32
	v_pk_mul_f32 v[36:37], v[30:31], v[32:33] op_sel_hi:[1,0]
	v_pk_mul_f32 v[30:31], v[28:29], v[32:33] op_sel_hi:[1,0]
	v_lshl_add_u64 v[28:29], s[16:17], 0, v[38:39]
	s_and_saveexec_b64 s[36:37], vcc
	s_cbranch_execz .LBB0_395
	v_lshl_add_u64 v[38:39], v[132:133], 3, v[28:29]
	global_load_dwordx4 v[38:41], v[38:39], off
	s_waitcnt vmcnt(0)
	v_pk_mul_f32 v[44:45], v[30:31], v[38:39] op_sel:[1,1] op_sel_hi:[0,1]
	v_mul_f32_e32 v46, v37, v41
	v_mul_f32_e32 v48, v36, v41
	v_pk_mul_f32 v[42:43], v[30:31], v[38:39]
	v_pk_fma_f32 v[30:31], v[30:31], v[38:39], v[44:45] op_sel_hi:[1,0,1]
	v_pk_fma_f32 v[38:39], v[36:37], v[40:41], v[46:47] op_sel_hi:[1,1,0] neg_lo:[0,0,1] neg_hi:[0,0,1]
	v_pk_fma_f32 v[40:41], v[36:37], v[40:41], v[48:49] op_sel:[1,0,0] op_sel_hi:[0,1,0]
	v_sub_f32_e32 v30, v42, v44
	v_mov_b32_e32 v36, v38
	v_mov_b32_e32 v37, v40

.LBB0_401:
	s_or_b64 exec, exec, s[36:37]
	v_cvt_pk_bf16_f32 v16, v16, v17
	v_cvt_pk_bf16_f32 v17, v18, v19
	v_add_u32_e32 v18, 0xb0, v144
	v_ashrrev_i32_e32 v19, 31, v18
	global_store_dwordx2 v[30:31], v[16:17], off offset:288
	v_lshl_add_u64 v[16:17], v[18:19], 2, s[66:67]
	v_mov_b32_e32 v16, v240
	v_lshlrev_b64 v[22:23], 8, v[18:19]
	v_mul_f32_e32 v16, 0x3dd53b94, v16
	v_pk_mul_f32 v[20:21], v[14:15], v[16:17] op_sel_hi:[1,0]
	v_pk_mul_f32 v[14:15], v[12:13], v[16:17] op_sel_hi:[1,0]
	v_lshl_add_u64 v[12:13], s[16:17], 0, v[22:23]
	s_and_saveexec_b64 s[36:37], vcc
	s_cbranch_execz .LBB0_403
	v_lshl_add_u64 v[22:23], v[132:133], 3, v[12:13]
	global_load_dwordx4 v[22:25], v[22:23], off
	s_waitcnt vmcnt(0)
	v_pk_mul_f32 v[28:29], v[14:15], v[22:23] op_sel:[1,1] op_sel_hi:[0,1]
	v_mul_f32_e32 v30, v21, v25
	v_mul_f32_e32 v32, v20, v25
	v_pk_mul_f32 v[26:27], v[14:15], v[22:23]
	v_pk_fma_f32 v[14:15], v[14:15], v[22:23], v[28:29] op_sel_hi:[1,0,1]
	v_pk_fma_f32 v[22:23], v[20:21], v[24:25], v[30:31] op_sel_hi:[1,1,0] neg_lo:[0,0,1] neg_hi:[0,0,1]
	v_pk_fma_f32 v[24:25], v[20:21], v[24:25], v[32:33] op_sel:[1,0,0] op_sel_hi:[0,1,0]
	v_sub_f32_e32 v14, v26, v28
	v_mov_b32_e32 v20, v22
	v_mov_b32_e32 v21, v24
